# P3 per-unit trims: first-tile packs written directly in the loop's P layout (no conversion moves), 64-bit accumulator zero-init
# speedup vs baseline: 1.0028x; 1.0028x over previous
.LBB0_318:
	s_or_b32 s0, s78, 31
	s_or_b32 s1, s2, 64
	s_cmp_gt_u32 s1, s0
	s_cselect_b64 s[70:71], -1, 0
	s_cmp_lg_u64 s[70:71], 0
	s_subb_u32 s82, s33, 0
	s_sub_i32 s0, s72, s2
	v_cvt_f32_i32_e32 v38, s0
	v_lshrrev_b32_e32 v35, 2, v35
	v_lshlrev_b32_e32 v45, 1, v211
	v_and_b32_e32 v44, 12, v33
	v_fma_f32 v40, v208, v38, -v207
	v_fmamk_f32 v41, v208, 0x42000000, v40
	v_add_f32_e32 v16, v40, v16
	v_add_f32_e32 v0, v41, v0
	v_exp_f32_e32 v42, v16
	v_exp_f32_e32 v43, v0
	v_add_f32_e32 v0, v40, v17
	v_add_f32_e32 v1, v41, v1
	v_exp_f32_e32 v0, v0
	v_exp_f32_e32 v16, v1
	v_add_f32_e32 v17, v43, v42
	v_mov_b32_e32 v1, v113
	v_add_f32_e32 v2, v41, v2
	v_pk_add_f32 v[38:39], v[16:17], v[0:1]
	v_add_f32_e32 v1, v40, v18
	v_pk_add_f32 v[38:39], v[38:39], v[38:39] op_sel_hi:[0,1]
	v_exp_f32_e32 v17, v2
	v_add_f32_e32 v2, v40, v19
	v_exp_f32_e32 v1, v1
	v_exp_f32_e32 v38, v2
	v_add_f32_e32 v2, v41, v3
	v_exp_f32_e32 v2, v2
	v_add_f32_e32 v3, v17, v1
	v_add_f32_e32 v4, v41, v4
	v_add_f32_e32 v6, v41, v6
	v_pk_add_f32 v[18:19], v[2:3], v[38:39]
	v_add_f32_e32 v3, v40, v20
	v_pk_add_f32 v[18:19], v[18:19], v[18:19] op_sel_hi:[0,1]
	v_exp_f32_e32 v39, v4
	v_add_f32_e32 v4, v40, v21
	v_exp_f32_e32 v3, v3
	v_exp_f32_e32 v18, v4
	v_add_f32_e32 v4, v41, v5
	v_exp_f32_e32 v4, v4
	v_or_b32_e32 v5, v34, v35
	v_lshlrev_b32_e32 v35, 8, v5
	v_add_f32_e32 v5, v39, v3
	v_pk_add_f32 v[20:21], v[4:5], v[18:19]
	v_add_f32_e32 v5, v40, v22
	v_pk_add_f32 v[20:21], v[20:21], v[20:21] op_sel_hi:[0,1]
	v_exp_f32_e32 v19, v6
	v_add_f32_e32 v6, v40, v23
	v_exp_f32_e32 v5, v5
	v_exp_f32_e32 v20, v6
	v_add_f32_e32 v6, v41, v7
	v_exp_f32_e32 v6, v6
	v_add_f32_e32 v7, v19, v5
	v_add_f32_e32 v8, v41, v8
	v_add_f32_e32 v10, v41, v10
	v_pk_add_f32 v[22:23], v[6:7], v[20:21]
	v_add_f32_e32 v7, v40, v24
	v_pk_add_f32 v[22:23], v[22:23], v[22:23] op_sel_hi:[0,1]
	v_exp_f32_e32 v21, v8
	v_add_f32_e32 v8, v40, v25
	v_exp_f32_e32 v7, v7
	v_exp_f32_e32 v22, v8
	v_add_f32_e32 v8, v41, v9
	v_exp_f32_e32 v8, v8
	v_add_f32_e32 v9, v21, v7
	v_and_b32_e32 v45, 2, v45
	v_and_b32_e32 v37, 1, v37
	v_pk_add_f32 v[24:25], v[8:9], v[22:23]
	v_add_f32_e32 v9, v40, v26
	v_pk_add_f32 v[24:25], v[24:25], v[24:25] op_sel_hi:[0,1]
	v_exp_f32_e32 v23, v10
	v_add_f32_e32 v10, v40, v27
	v_exp_f32_e32 v9, v9
	v_exp_f32_e32 v24, v10
	v_add_f32_e32 v10, v41, v11
	v_exp_f32_e32 v10, v10
	v_or3_b32 v11, v44, v45, v37
	v_lshlrev_b32_e32 v37, 4, v11
	v_add_f32_e32 v11, v23, v9
	v_pk_add_f32 v[26:27], v[10:11], v[24:25]
	v_add_f32_e32 v12, v41, v12
	v_pk_add_f32 v[26:27], v[26:27], v[26:27] op_sel_hi:[0,1]
	v_add_f32_e32 v11, v40, v28
	v_exp_f32_e32 v25, v12
	v_add_f32_e32 v12, v40, v29
	v_exp_f32_e32 v11, v11
	v_exp_f32_e32 v26, v12
	v_add_f32_e32 v12, v41, v13
	v_exp_f32_e32 v12, v12
	v_lshlrev_b32_e32 v13, 3, v33
	v_and_b32_e32 v33, 8, v13
	v_add_f32_e32 v13, v25, v11
	v_pk_add_f32 v[28:29], v[12:13], v[26:27]
	v_add_f32_e32 v14, v41, v14
	v_pk_add_f32 v[28:29], v[28:29], v[28:29] op_sel_hi:[0,1]
	v_add_f32_e32 v13, v40, v30
	v_exp_f32_e32 v27, v14
	v_add_f32_e32 v14, v40, v31
	v_exp_f32_e32 v13, v13
	v_exp_f32_e32 v28, v14
	v_add_f32_e32 v14, v41, v15
	v_exp_f32_e32 v14, v14
	v_add_f32_e32 v15, v27, v13
	v_or3_b32 v235, v37, v35, v33
	s_mov_b32 s72, 0
	v_pk_add_f32 v[30:31], v[14:15], v[28:29]
	v_cvt_pk_bf16_f32 v174, v42, v0
	v_cvt_pk_bf16_f32 v175, v1, v38
	v_cvt_pk_bf16_f32 v176, v3, v18
	v_cvt_pk_bf16_f32 v177, v5, v20
	v_cvt_pk_bf16_f32 v162, v7, v22
	s_nop 0
	v_add_f32_e32 v15, v30, v31
	v_add_f32_e32 v229, 0, v15
	v_cvt_pk_bf16_f32 v163, v9, v24
	v_cvt_pk_bf16_f32 v164, v11, v26
	v_cvt_pk_bf16_f32 v165, v13, v28
	v_cvt_pk_bf16_f32 v170, v43, v16
	v_cvt_pk_bf16_f32 v171, v17, v2
	v_cvt_pk_bf16_f32 v172, v39, v4
	v_cvt_pk_bf16_f32 v173, v19, v6
	v_cvt_pk_bf16_f32 v166, v21, v8
	v_cvt_pk_bf16_f32 v167, v23, v10
	v_cvt_pk_bf16_f32 v168, v25, v12
	v_cvt_pk_bf16_f32 v169, v27, v14
	s_cmp_lt_i32 s82, 2
	v_xor_b32_e32 v236, 0x80, v235
	v_xor_b32_e32 v234, 0xc0, v235
	s_cbranch_scc1 .LBB0_331
	s_mov_b32 s97, s83
	s_lshl_b64 s[0:1], s[96:97], 13
	v_lshl_add_u64 v[0:1], v[212:213], 0, s[0:1]
	s_mov_b64 s[0:1], 0x106000
	v_lshl_add_u64 v[218:219], v[0:1], 0, s[0:1]
	s_mov_b64 s[0:1], 0x6000
	v_lshl_add_u64 v[220:221], v[0:1], 0, s[0:1]
	s_lshl_b64 s[0:1], s[96:97], 14
	v_lshl_add_u64 v[0:1], v[214:215], 0, s[0:1]
	s_mov_b64 s[4:5], 0xc000
	v_lshl_add_u64 v[222:223], v[0:1], 0, s[4:5]
	v_lshl_add_u64 v[0:1], v[216:217], 0, s[0:1]
	v_readlane_b32 s1, v244, 25
	s_add_i32 s1, s1, s2
	v_lshl_add_u64 v[224:225], v[0:1], 0, s[4:5]
	v_add_u32_e32 v0, s1, v32
	s_lshl_b32 s0, s96, 6
	v_sub_u32_e32 v0, v0, v34
	s_add_i32 s97, s0, 0x7f
	v_subrev_u32_e32 v240, s0, v0
	s_and_b32 s0, s74, 63
	s_lshl_b32 s0, s0, 7
	v_mul_f32_e32 v237, 0x42000000, v208
	v_add_u32_e32 v238, 0, v36
	v_xor_b32_e32 v239, 64, v235
	s_add_i32 s73, s33, -2
	s_add_i32 s79, s77, 0x18000
	s_sub_i32 s74, 0, s0
	v_mov_b64_e32 v[0:1], 0
	v_mov_b64_e32 v[2:3], 0
	v_mov_b64_e32 v[4:5], 0
	v_mov_b64_e32 v[6:7], 0
	v_mov_b64_e32 v[8:9], 0
	v_mov_b64_e32 v[10:11], 0
	v_mov_b64_e32 v[12:13], 0
	v_mov_b64_e32 v[14:15], 0
	v_mov_b64_e32 v[16:17], 0
	v_mov_b64_e32 v[18:19], 0
	v_mov_b64_e32 v[20:21], 0
	v_mov_b64_e32 v[22:23], 0
	v_mov_b64_e32 v[24:25], 0
	v_mov_b64_e32 v[26:27], 0
	v_mov_b64_e32 v[28:29], 0
	v_mov_b64_e32 v[30:31], 0
	v_mov_b64_e32 v[32:33], 0
	v_mov_b64_e32 v[34:35], 0
	v_mov_b64_e32 v[36:37], 0
	v_mov_b64_e32 v[38:39], 0
	v_mov_b64_e32 v[40:41], 0
	v_mov_b64_e32 v[42:43], 0
	v_mov_b64_e32 v[44:45], 0
	v_mov_b64_e32 v[46:47], 0
	v_mov_b64_e32 v[48:49], 0
	v_mov_b64_e32 v[50:51], 0
	v_mov_b64_e32 v[52:53], 0
	v_mov_b64_e32 v[54:55], 0
	v_mov_b64_e32 v[56:57], 0
	v_mov_b64_e32 v[58:59], 0
	v_mov_b64_e32 v[60:61], 0
	v_mov_b64_e32 v[62:63], 0
	v_add_u32_e32 v222, v238, v230
	v_add_u32_e32 v223, v238, v231
	v_add_u32_e32 v241, v238, v232
	v_add_u32_e32 v242, v238, v233
	s_sub_i32 s101, s78, s97
	s_ashr_i32 s101, s101, 6
	s_add_i32 s98, s33, -3
	s_add_i32 s99, s82, -1
	s_add_i32 s100, s74, s97
	s_sub_i32 s100, s100, 63
	v_cvt_f32_i32_e32 v156, s100
	v_add_f32_e32 v156, v255, v156
	v_fma_f32 v254, v208, v156, -v207
	v_mov_b32_e32 v64, v254
	v_fmamk_f32 v65, v208, 0x3f800000, v254
	v_fmamk_f32 v66, v208, 0x40000000, v254
	v_fmamk_f32 v67, v208, 0x40400000, v254
	v_fmamk_f32 v68, v208, 0x41000000, v254
	v_fmamk_f32 v69, v208, 0x41100000, v254
	v_fmamk_f32 v70, v208, 0x41200000, v254
	v_fmamk_f32 v71, v208, 0x41300000, v254
	v_fmamk_f32 v72, v208, 0x41800000, v254
	v_fmamk_f32 v73, v208, 0x41880000, v254
	v_fmamk_f32 v74, v208, 0x41900000, v254
	v_fmamk_f32 v75, v208, 0x41980000, v254
	v_fmamk_f32 v76, v208, 0x41c00000, v254
	v_fmamk_f32 v77, v208, 0x41c80000, v254
	v_fmamk_f32 v78, v208, 0x41d00000, v254
	v_fmamk_f32 v79, v208, 0x41d80000, v254
	s_cmp_ge_i32 s72, s73
	s_mov_b64 s[0:1], -1
	s_cbranch_scc0 .LBB0_321

.LBB0_331:
	v_mov_b64_e32 v[0:1], 0
	v_mov_b64_e32 v[2:3], 0
	v_mov_b64_e32 v[4:5], 0
	v_mov_b64_e32 v[6:7], 0
	v_mov_b64_e32 v[8:9], 0
	v_mov_b64_e32 v[10:11], 0
	v_mov_b64_e32 v[12:13], 0
	v_mov_b64_e32 v[14:15], 0
	v_mov_b64_e32 v[16:17], 0
	v_mov_b64_e32 v[18:19], 0
	v_mov_b64_e32 v[20:21], 0
	v_mov_b64_e32 v[22:23], 0
	v_mov_b64_e32 v[24:25], 0
	v_mov_b64_e32 v[26:27], 0
	v_mov_b64_e32 v[28:29], 0
	v_mov_b64_e32 v[30:31], 0
	v_mov_b64_e32 v[32:33], 0
	v_mov_b64_e32 v[34:35], 0
	v_mov_b64_e32 v[36:37], 0
	v_mov_b64_e32 v[38:39], 0
	v_mov_b64_e32 v[40:41], 0
	v_mov_b64_e32 v[42:43], 0
	v_mov_b64_e32 v[44:45], 0
	v_mov_b64_e32 v[46:47], 0
	v_mov_b64_e32 v[48:49], 0
	v_mov_b64_e32 v[50:51], 0
	v_mov_b64_e32 v[52:53], 0
	v_mov_b64_e32 v[54:55], 0
	v_mov_b64_e32 v[56:57], 0
	v_mov_b64_e32 v[58:59], 0
	v_mov_b64_e32 v[60:61], 0
	v_mov_b64_e32 v[62:63], 0
	s_branch .LBB0_333
.LBB0_332:
	v_readlane_b32 s79, v244, 28

.LBB0_337:
	s_add_i32 s82, s82, s75
	s_lshl_b32 s0, s82, 15
	s_addk_i32 s0, 0x8000
	s_and_b32 s0, s0, 0x18000
	s_add_i32 s0, s0, 0
	v_add_u32_e32 v72, s0, v235
	v_xad_u32 v73, v235, 64, s0
	v_add_u32_e32 v74, s0, v236
	v_add_u32_e32 v75, s0, v234
	ds_read_b64_tr_b16 v[64:65], v72 offset:32768
	ds_read_b64_tr_b16 v[66:67], v72 offset:34816
	ds_read_b64_tr_b16 v[68:69], v72 offset:36864
	ds_read_b64_tr_b16 v[70:71], v72 offset:38912
	ds_read_b64_tr_b16 v[76:77], v72 offset:40960
	ds_read_b64_tr_b16 v[78:79], v72 offset:43008
	s_waitcnt lgkmcnt(4)
	v_mfma_f32_32x32x16_bf16 v[48:63], v[64:67], v[174:177], v[48:63]
	ds_read_b64_tr_b16 v[64:65], v72 offset:45056
	ds_read_b64_tr_b16 v[66:67], v72 offset:47104
	s_waitcnt lgkmcnt(4)
	v_mfma_f32_32x32x16_bf16 v[48:63], v[68:71], v[162:165], v[48:63]
	ds_read_b64_tr_b16 v[68:69], v73 offset:32768
	ds_read_b64_tr_b16 v[70:71], v73 offset:34816
	s_waitcnt lgkmcnt(4)
	v_mfma_f32_32x32x16_bf16 v[48:63], v[76:79], v[170:173], v[48:63]
	ds_read_b64_tr_b16 v[76:77], v73 offset:36864
	ds_read_b64_tr_b16 v[78:79], v73 offset:38912
	s_waitcnt lgkmcnt(4)
	v_mfma_f32_32x32x16_bf16 v[48:63], v[64:67], v[166:169], v[48:63]
	ds_read_b64_tr_b16 v[64:65], v73 offset:40960
	ds_read_b64_tr_b16 v[66:67], v73 offset:43008
	s_waitcnt lgkmcnt(4)
	v_mfma_f32_32x32x16_bf16 v[32:47], v[68:71], v[174:177], v[32:47]
	ds_read_b64_tr_b16 v[68:69], v73 offset:45056
	ds_read_b64_tr_b16 v[70:71], v73 offset:47104
	s_waitcnt lgkmcnt(4)
	v_mfma_f32_32x32x16_bf16 v[32:47], v[76:79], v[162:165], v[32:47]
	ds_read_b64_tr_b16 v[76:77], v74 offset:32768
	ds_read_b64_tr_b16 v[78:79], v74 offset:34816
	s_waitcnt lgkmcnt(4)
	v_mfma_f32_32x32x16_bf16 v[32:47], v[64:67], v[170:173], v[32:47]
	ds_read_b64_tr_b16 v[64:65], v74 offset:36864
	ds_read_b64_tr_b16 v[66:67], v74 offset:38912
	s_waitcnt lgkmcnt(4)
	v_mfma_f32_32x32x16_bf16 v[32:47], v[68:71], v[166:169], v[32:47]
	ds_read_b64_tr_b16 v[68:69], v74 offset:40960
	ds_read_b64_tr_b16 v[70:71], v74 offset:43008
	s_waitcnt lgkmcnt(4)
	v_mfma_f32_32x32x16_bf16 v[16:31], v[76:79], v[174:177], v[16:31]
	ds_read_b64_tr_b16 v[76:77], v74 offset:45056
	ds_read_b64_tr_b16 v[78:79], v74 offset:47104
	s_waitcnt lgkmcnt(4)
	v_mfma_f32_32x32x16_bf16 v[16:31], v[64:67], v[162:165], v[16:31]
	ds_read_b64_tr_b16 v[64:65], v75 offset:32768
	ds_read_b64_tr_b16 v[66:67], v75 offset:34816
	s_waitcnt lgkmcnt(4)
	v_mfma_f32_32x32x16_bf16 v[16:31], v[68:71], v[170:173], v[16:31]
	ds_read_b64_tr_b16 v[68:69], v75 offset:36864
	ds_read_b64_tr_b16 v[70:71], v75 offset:38912
	s_waitcnt lgkmcnt(4)
	v_mfma_f32_32x32x16_bf16 v[16:31], v[76:79], v[166:169], v[16:31]
	ds_read_b64_tr_b16 v[76:77], v75 offset:40960
	ds_read_b64_tr_b16 v[78:79], v75 offset:43008
	s_waitcnt lgkmcnt(4)
	v_mfma_f32_32x32x16_bf16 v[0:15], v[64:67], v[174:177], v[0:15]
	ds_read_b64_tr_b16 v[64:65], v75 offset:45056
	ds_read_b64_tr_b16 v[66:67], v75 offset:47104
	s_waitcnt lgkmcnt(4)
	v_mfma_f32_32x32x16_bf16 v[0:15], v[68:71], v[162:165], v[0:15]
	s_waitcnt lgkmcnt(2)
	v_mfma_f32_32x32x16_bf16 v[0:15], v[76:79], v[170:173], v[0:15]
	s_waitcnt lgkmcnt(0)
	v_mfma_f32_32x32x16_bf16 v[0:15], v[64:67], v[166:169], v[0:15]
	s_andn2_b64 vcc, exec, s[70:71]
	v_readlane_b32 s33, v244, 31
	s_cbranch_vccnz .LBB0_339
	s_waitcnt vmcnt(0) lgkmcnt(0)
	s_barrier
